# P2 NOMAX loop: the two '0 + sum' adds folded into the chain's last add (2 fewer VALU per iteration) and the s[98:99] SALU pair moved from the loop top to behind the first MFMA, on top of P1 LDS tables
# speedup vs baseline: 1.0103x; 1.0040x over previous
; __device__ __forceinline__ void glds16(const void*gsrc,unsigned lds_dst){unsigned keep;
;   asm volatile("s_mov_b32 %0, m0\n\ts_mov_b32 m0, %2\n\ts_nop 0\n\tglobal_load_lds_dwordx4 %1, off\n\ts_mov_b32 m0, %0":"=&s"(keep):"v"(gsrc),"s"(lds_dst):"memory");}
.LBB0_1097:
	s_mov_b32 s7, s89
	s_mov_b32 s88, s38
	s_mov_b32 s37, s87
	v_add_u32_e32 v198, s36, v233
	ds_read_b64_tr_b16 v[200:201], v198 offset:24576
	ds_read_b64_tr_b16 v[202:203], v198 offset:25088
	v_add_f32_e32 v98, v82, v83
	v_add_f32_e32 v98, v84, v98
	v_add_f32_e32 v98, v85, v98
	v_add_f32_e32 v98, v86, v98
	v_add_f32_e32 v98, v87, v98
	v_cvt_pk_bf16_f32 v158, v82, v83
	v_cvt_pk_bf16_f32 v159, v84, v85
	s_waitcnt lgkmcnt(9)
	v_mfma_f32_32x32x16_bf16 v[114:129], v[190:193], v[130:133], v[50:65]
	s_add_u32 s98, s100, s24
	s_addc_u32 s99, s101, s25
	ds_read_b64_tr_b16 v[82:83], v198 offset:28672
	ds_read_b64_tr_b16 v[84:85], v198 offset:29184
	v_add_f32_e32 v98, v88, v98
	v_add_f32_e32 v98, v89, v98
	v_add_f32_e32 v98, v90, v98
	v_add_f32_e32 v146, v91, v98
	s_waitcnt lgkmcnt(10)
	v_mfma_f32_32x32x16_bf16 v[98:113], v[186:189], v[130:133], v[50:65]
	v_cvt_pk_bf16_f32 v160, v86, v87
	v_cvt_pk_bf16_f32 v161, v88, v89
	ds_read_b64_tr_b16 v[86:87], v198 offset:25600
	ds_read_b64_tr_b16 v[88:89], v198 offset:26112
	v_add_f32_e32 v146, v92, v146
	v_add_f32_e32 v146, v93, v146
	v_add_f32_e32 v146, v94, v146
	v_add_f32_e32 v146, v95, v146
	v_cvt_pk_bf16_f32 v154, v90, v91
	v_cvt_pk_bf16_f32 v155, v92, v93
	s_waitcnt lgkmcnt(11)
	v_mfma_f32_32x32x16_bf16 v[114:129], v[182:185], v[134:137], v[114:129]
	ds_read_b64_tr_b16 v[90:91], v198 offset:29696
	ds_read_b64_tr_b16 v[92:93], v198 offset:30208
	s_waitcnt lgkmcnt(12)
	v_mfma_f32_32x32x16_bf16 v[98:113], v[178:181], v[134:137], v[98:113]
	v_add_f32_e32 v146, v96, v146
	v_add_f32_e32 v146, v97, v146
	v_add_f32_e32 v146, v66, v146
	v_add_f32_e32 v146, v67, v146
	v_cvt_pk_bf16_f32 v156, v94, v95
	v_cvt_pk_bf16_f32 v157, v96, v97
	ds_read_b64_tr_b16 v[94:95], v198 offset:26624
	ds_read_b64_tr_b16 v[96:97], v198 offset:27136
	v_add_f32_e32 v146, v68, v146
	v_add_f32_e32 v146, v69, v146
	v_add_f32_e32 v146, v70, v146
	v_add_f32_e32 v146, v71, v146
	v_cvt_pk_bf16_f32 v150, v66, v67
	v_cvt_pk_bf16_f32 v151, v68, v69
	s_waitcnt lgkmcnt(13)
	v_mfma_f32_32x32x16_bf16 v[114:129], v[174:177], v[138:141], v[114:129]
	ds_read_b64_tr_b16 v[66:67], v198 offset:30720
	ds_read_b64_tr_b16 v[68:69], v198 offset:31232
	s_waitcnt lgkmcnt(14)
	v_mfma_f32_32x32x16_bf16 v[98:113], v[170:173], v[138:141], v[98:113]
	v_add_f32_e32 v146, v72, v146
	v_add_f32_e32 v146, v73, v146
	v_add_f32_e32 v146, v74, v146
	v_add_f32_e32 v146, v75, v146
	v_cvt_pk_bf16_f32 v152, v70, v71
	v_cvt_pk_bf16_f32 v153, v72, v73
	ds_read_b64_tr_b16 v[70:71], v198 offset:27648
	ds_read_b64_tr_b16 v[72:73], v198 offset:28160
	v_add_f32_e32 v146, v76, v146
	v_add_f32_e32 v146, v77, v146
	v_add_f32_e32 v146, v78, v146
	v_add_f32_e32 v170, v79, v146
	v_cvt_pk_bf16_f32 v146, v74, v75
	v_cvt_pk_bf16_f32 v147, v76, v77
	s_waitcnt lgkmcnt(14)
	v_mfma_f32_32x32x16_bf16 v[114:129], v[166:169], v[142:145], v[114:129]
	ds_read_b64_tr_b16 v[74:75], v198 offset:31744
	ds_read_b64_tr_b16 v[76:77], v198 offset:32256
	v_mfma_f32_32x32x16_bf16 v[98:113], v[162:165], v[142:145], v[98:113]
	v_add_f32_e32 v148, v80, v170
	v_add_f32_e32 v198, v81, v148
	v_cvt_pk_bf16_f32 v148, v78, v79
	v_cvt_pk_bf16_f32 v149, v80, v81
	s_add_i32 s0, s87, s84
	s_mov_b32 s1, m0
	s_mov_b32 m0, s0
	s_nop 0
	global_load_lds_dwordx4 v196, s[98:99]
	s_mov_b32 m0, s1
	s_add_i32 s0, s89, s8
	s_mov_b32 s1, m0
	s_mov_b32 m0, s0
	s_nop 0
	global_load_lds_dwordx4 v194, s[98:99]
	s_mov_b32 m0, s1
	s_waitcnt lgkmcnt(14)
	v_mfma_f32_32x32x16_bf16 v[18:33], v[158:161], v[200:203], v[18:33]
	v_exp_f32_e32 v114, v114
	v_exp_f32_e32 v115, v115
	v_exp_f32_e32 v116, v116
	v_exp_f32_e32 v117, v117
	s_waitcnt lgkmcnt(12)
	v_mfma_f32_32x32x16_bf16 v[34:49], v[158:161], v[82:85], v[34:49]
	v_exp_f32_e32 v118, v118
	v_exp_f32_e32 v119, v119
	v_exp_f32_e32 v120, v120
	v_exp_f32_e32 v121, v121
	v_add_u32_e32 v82, s7, v232
	ds_read_b128 v[78:81], v82
	ds_read_b128 v[162:165], v82 offset:512
	s_waitcnt lgkmcnt(12)
	v_mfma_f32_32x32x16_bf16 v[18:33], v[154:157], v[86:89], v[18:33]
	v_exp_f32_e32 v122, v122
	v_exp_f32_e32 v123, v123
	v_exp_f32_e32 v124, v124
	v_exp_f32_e32 v125, v125
	ds_read_b128 v[166:169], v82 offset:2048
	ds_read_b128 v[170:173], v82 offset:2560
	s_waitcnt lgkmcnt(12)
	v_mfma_f32_32x32x16_bf16 v[34:49], v[154:157], v[90:93], v[34:49]
	v_exp_f32_e32 v126, v126
	v_exp_f32_e32 v127, v127
	v_exp_f32_e32 v128, v128
	v_exp_f32_e32 v129, v129
	ds_read_b128 v[174:177], v82 offset:4096
	ds_read_b128 v[178:181], v82 offset:4608
	s_waitcnt lgkmcnt(12)
	v_mfma_f32_32x32x16_bf16 v[18:33], v[150:153], v[94:97], v[18:33]
	v_exp_f32_e32 v98, v98
	v_exp_f32_e32 v99, v99
	v_exp_f32_e32 v100, v100
	v_exp_f32_e32 v101, v101
	ds_read_b128 v[182:185], v82 offset:6144
	ds_read_b128 v[186:189], v82 offset:6656
	s_waitcnt lgkmcnt(12)
	v_mfma_f32_32x32x16_bf16 v[34:49], v[150:153], v[66:69], v[34:49]
	v_exp_f32_e32 v102, v102
	v_exp_f32_e32 v103, v103
	v_exp_f32_e32 v104, v104
	v_exp_f32_e32 v105, v105
	s_waitcnt lgkmcnt(10)
	v_mfma_f32_32x32x16_bf16 v[18:33], v[146:149], v[70:73], v[18:33]
	v_exp_f32_e32 v106, v106
	v_exp_f32_e32 v107, v107
	v_exp_f32_e32 v108, v108
	v_exp_f32_e32 v109, v109
	s_waitcnt lgkmcnt(8)
	v_mfma_f32_32x32x16_bf16 v[34:49], v[146:149], v[74:77], v[34:49]
	v_exp_f32_e32 v110, v110
	v_exp_f32_e32 v111, v111
	v_exp_f32_e32 v112, v112
	v_exp_f32_e32 v113, v113
	s_waitcnt vmcnt(2) lgkmcnt(0)
	s_barrier
; #define WAIT_BAR(N) asm volatile("s_waitcnt vmcnt(" #N ") lgkmcnt(0)\n\ts_barrier":::"memory")
;   #define RESC() do{ if(resc){ asm volatile("s_waitcnt lgkmcnt(0)":::"memory"); \
;       _Pragma("unroll") for(int d_=0;d_<2;++d_) _Pragma("unroll") for(int r=0;r<16;++r)o[d_][r]*=wsf[crow(r,hi)]; } }while(0)
;   #define ROT() do{sl_prev=sl_cur;sl_cur=sl_next;sl_next=(sl_next==(NSLOT-1)*SLOTB)?0:sl_next+SLOTB;}while(0)
; template<int THRL,bool NOMAX> __device__ __forceinline__ void attn_unit(long rowbase,int NT,int h,int qb,const bf16*Q,const bf16*__restrict__ Kh,const bf16*__restrict__ Vh,bf16*O,char*shm,
;     bool first,bool has_next,long n_rowbase,int n_h,int n_qb,const bf16*__restrict__ n_Kh,bf16x8 (&qr)[4]){
;     ...
;   for(;t+5<NT;t+=2){
;     STEP(pB0,pB1,pA0,pA1,t,true,true,true);     WAIT_BAR(2); RESC(); ROT();
;     STEP(pA0,pA1,pB0,pB1,t+1,true,true,true);   WAIT_BAR(2); RESC(); ROT();
;   }
	s_add_i32 s0, s89, 0x2000
	s_cmpk_lg_i32 s89, 0x4000
	s_cselect_b32 s87, s0, 0
	v_add_u32_e32 v199, s37, v233
	ds_read_b64_tr_b16 v[190:191], v199 offset:24576
	ds_read_b64_tr_b16 v[192:193], v199 offset:25088
	s_waitcnt lgkmcnt(9)
	v_mfma_f32_32x32x16_bf16 v[82:97], v[78:81], v[130:133], v[50:65]
	v_add_f32_e32 v66, v114, v115
	v_add_f32_e32 v66, v116, v66
	v_add_f32_e32 v66, v117, v66
	v_add_f32_e32 v66, v118, v66
	v_add_f32_e32 v66, v119, v66
	v_cvt_pk_bf16_f32 v158, v114, v115
	v_cvt_pk_bf16_f32 v159, v116, v117
	ds_read_b64_tr_b16 v[114:115], v199 offset:28672
	ds_read_b64_tr_b16 v[116:117], v199 offset:29184
	v_add_f32_e32 v66, v120, v66
	v_add_f32_e32 v66, v121, v66
	v_add_f32_e32 v66, v122, v66
	v_add_f32_e32 v146, v123, v66
	s_waitcnt lgkmcnt(10)
	v_mfma_f32_32x32x16_bf16 v[66:81], v[162:165], v[130:133], v[50:65]
	v_cvt_pk_bf16_f32 v160, v118, v119
	v_cvt_pk_bf16_f32 v161, v120, v121
	ds_read_b64_tr_b16 v[118:119], v199 offset:25600
	ds_read_b64_tr_b16 v[120:121], v199 offset:26112
	s_waitcnt lgkmcnt(11)
	v_mfma_f32_32x32x16_bf16 v[82:97], v[166:169], v[134:137], v[82:97]
	v_add_f32_e32 v146, v124, v146
	v_add_f32_e32 v146, v125, v146
	v_add_f32_e32 v146, v126, v146
	v_add_f32_e32 v146, v127, v146
	v_cvt_pk_bf16_f32 v154, v122, v123
	v_cvt_pk_bf16_f32 v155, v124, v125
	ds_read_b64_tr_b16 v[122:123], v199 offset:29696
	ds_read_b64_tr_b16 v[124:125], v199 offset:30208
	s_waitcnt lgkmcnt(12)
	v_mfma_f32_32x32x16_bf16 v[66:81], v[170:173], v[134:137], v[66:81]
	v_add_f32_e32 v146, v128, v146
	v_add_f32_e32 v146, v129, v146
	v_add_f32_e32 v146, v98, v146
	v_add_f32_e32 v146, v99, v146
	v_cvt_pk_bf16_f32 v156, v126, v127
	v_cvt_pk_bf16_f32 v157, v128, v129
	ds_read_b64_tr_b16 v[126:127], v199 offset:26624
	ds_read_b64_tr_b16 v[128:129], v199 offset:27136
	s_waitcnt lgkmcnt(13)
	v_mfma_f32_32x32x16_bf16 v[82:97], v[174:177], v[138:141], v[82:97]
	v_add_f32_e32 v146, v100, v146
	v_add_f32_e32 v146, v101, v146
	v_add_f32_e32 v146, v102, v146
	v_add_f32_e32 v146, v103, v146
	v_cvt_pk_bf16_f32 v150, v98, v99
	v_cvt_pk_bf16_f32 v151, v100, v101
	ds_read_b64_tr_b16 v[98:99], v199 offset:30720
	ds_read_b64_tr_b16 v[100:101], v199 offset:31232
	s_waitcnt lgkmcnt(14)
	v_mfma_f32_32x32x16_bf16 v[66:81], v[178:181], v[138:141], v[66:81]
	v_add_f32_e32 v146, v104, v146
	v_add_f32_e32 v146, v105, v146
	v_add_f32_e32 v146, v106, v146
	v_add_f32_e32 v146, v107, v146
	v_cvt_pk_bf16_f32 v152, v102, v103
	v_cvt_pk_bf16_f32 v153, v104, v105
	ds_read_b64_tr_b16 v[102:103], v199 offset:27648
	ds_read_b64_tr_b16 v[104:105], v199 offset:28160
	s_waitcnt lgkmcnt(14)
	v_mfma_f32_32x32x16_bf16 v[82:97], v[182:185], v[142:145], v[82:97]
	v_add_f32_e32 v146, v108, v146
	v_add_f32_e32 v146, v109, v146
	v_add_f32_e32 v146, v110, v146
	v_add_f32_e32 v162, v111, v146
	v_cvt_pk_bf16_f32 v146, v106, v107
	v_cvt_pk_bf16_f32 v147, v108, v109
	ds_read_b64_tr_b16 v[106:107], v199 offset:31744
	ds_read_b64_tr_b16 v[108:109], v199 offset:32256
	v_mfma_f32_32x32x16_bf16 v[66:81], v[186:189], v[142:145], v[66:81]
	v_add_f32_e32 v148, v112, v162
	v_add_f32_e32 v199, v113, v148
	v_cvt_pk_bf16_f32 v148, v110, v111
	v_cvt_pk_bf16_f32 v149, v112, v113
	s_add_i32 s0, s89, s84
	s_mov_b32 s1, m0
	s_mov_b32 m0, s0
	s_nop 0
	global_load_lds_dwordx4 v196, s[100:101]
	s_mov_b32 m0, s1
	s_add_i32 s0, s87, s8
	s_mov_b32 s1, m0
	s_mov_b32 m0, s0
	s_nop 0
	global_load_lds_dwordx4 v194, s[100:101]
	s_mov_b32 m0, s1
	s_waitcnt lgkmcnt(14)
	v_mfma_f32_32x32x16_bf16 v[18:33], v[158:161], v[190:193], v[18:33]
	v_exp_f32_e32 v82, v82
	v_exp_f32_e32 v83, v83
	v_exp_f32_e32 v84, v84
	v_exp_f32_e32 v85, v85
	s_waitcnt lgkmcnt(12)
	v_mfma_f32_32x32x16_bf16 v[34:49], v[158:161], v[114:117], v[34:49]
	v_exp_f32_e32 v86, v86
	v_exp_f32_e32 v87, v87
	v_exp_f32_e32 v88, v88
	v_exp_f32_e32 v89, v89
	v_add_u32_e32 v110, s87, v232
	ds_read_b128 v[190:193], v110
	ds_read_b128 v[186:189], v110 offset:512
	s_waitcnt lgkmcnt(12)
	v_mfma_f32_32x32x16_bf16 v[18:33], v[154:157], v[118:121], v[18:33]
	v_exp_f32_e32 v90, v90
	v_exp_f32_e32 v91, v91
	v_exp_f32_e32 v92, v92
	v_exp_f32_e32 v93, v93
	ds_read_b128 v[182:185], v110 offset:2048
	ds_read_b128 v[178:181], v110 offset:2560
	s_waitcnt lgkmcnt(12)
	v_mfma_f32_32x32x16_bf16 v[34:49], v[154:157], v[122:125], v[34:49]
	v_exp_f32_e32 v94, v94
	v_exp_f32_e32 v95, v95
	v_exp_f32_e32 v96, v96
	v_exp_f32_e32 v97, v97
	ds_read_b128 v[174:177], v110 offset:4096
	ds_read_b128 v[170:173], v110 offset:4608
	s_waitcnt lgkmcnt(12)
	v_mfma_f32_32x32x16_bf16 v[18:33], v[150:153], v[126:129], v[18:33]
	v_exp_f32_e32 v66, v66
	v_exp_f32_e32 v67, v67
	v_exp_f32_e32 v68, v68
	v_exp_f32_e32 v69, v69
	ds_read_b128 v[166:169], v110 offset:6144
	ds_read_b128 v[162:165], v110 offset:6656
	s_waitcnt lgkmcnt(12)
	v_mfma_f32_32x32x16_bf16 v[34:49], v[150:153], v[98:101], v[34:49]
	v_exp_f32_e32 v70, v70
	v_exp_f32_e32 v71, v71
	v_exp_f32_e32 v72, v72
	v_exp_f32_e32 v73, v73
	s_waitcnt lgkmcnt(10)
	v_mfma_f32_32x32x16_bf16 v[18:33], v[146:149], v[102:105], v[18:33]
	v_exp_f32_e32 v74, v74
	v_exp_f32_e32 v75, v75
	v_exp_f32_e32 v76, v76
	v_exp_f32_e32 v77, v77
	s_waitcnt lgkmcnt(8)
	v_mfma_f32_32x32x16_bf16 v[34:49], v[146:149], v[106:109], v[34:49]
	v_exp_f32_e32 v78, v78
	v_exp_f32_e32 v79, v79
	v_exp_f32_e32 v80, v80
	v_exp_f32_e32 v81, v81
	s_add_i32 s0, s87, 0x2000
	s_waitcnt vmcnt(2) lgkmcnt(0)
	s_barrier
	s_cmpk_lg_i32 s87, 0x4000
	v_add_f32_e32 v102, v206, v198
	s_mov_b32 s36, s89
	s_cselect_b32 s89, s0, 0
	s_add_i32 s6, s6, 2
	s_add_i32 s38, s38, 2
	s_add_u32 s100, s100, s14
	s_addc_u32 s101, s101, s15
	s_cmp_ge_u32 s6, s82
	v_add_f32_e32 v206, v102, v199
	s_cbranch_scc0 .LBB0_1097
	s_sub_u32 s98, s100, s62
	s_subb_u32 s99, s101, s63
	s_sub_u32 s98, s98, s14
	s_subb_u32 s99, s99, s15
	v_lshl_add_u64 v[226:227], v[226:227], 0, s[98:99]
	v_lshl_add_u64 v[228:229], v[228:229], 0, s[98:99]
	s_add_i32 s0, s6, -4
	s_cmp_ge_u32 s0, s82
	s_cbranch_scc1 .LBB0_1132
	s_add_i32 s90, s6, -5
